# P0 fully hand-rewritten (weights + x conversion, 32-48 KB in flight per wave), final rmsnorm rewritten (gains loaded once, 8 rows in flight)
# speedup vs baseline: 1.0396x; 1.0011x over previous
.Lwt_done:
.LBB0_178:
	v_readlane_b32 s8, v253, 0
	v_readlane_b32 s10, v253, 2
	v_readlane_b32 s11, v253, 3
	s_add_u32 s46, s10, 0x3400000
	s_addc_u32 s47, s11, 0
	s_cmpk_lt_i32 s36, 0x4200
	s_cselect_b64 s[0:1], -1, 0
	v_readlane_b32 s9, v253, 1
	v_writelane_b32 v253, s0, 46
	s_cmpk_gt_i32 s36, 0x41ff
	v_mbcnt_lo_u32_b32 v42, -1, 0
	v_writelane_b32 v253, s1, 47
	s_cbranch_scc1 .LBB0_192
	v_mbcnt_hi_u32_b32 v3, -1, v42
	s_ashr_i32 s39, s38, 31
	v_lshlrev_b32_e32 v4, 4, v227
	v_lshlrev_b32_e32 v5, 3, v227
	v_mov_b32_e32 v12, 0
	v_xor_b32_e32 v6, 1, v227
	v_lshlrev_b32_e32 v6, 2, v6
	v_xor_b32_e32 v7, 2, v227
	v_lshlrev_b32_e32 v7, 2, v7
	v_xor_b32_e32 v8, 4, v227
	v_lshlrev_b32_e32 v8, 2, v8
	v_xor_b32_e32 v9, 8, v227
	v_lshlrev_b32_e32 v9, 2, v9
	v_xor_b32_e32 v10, 16, v227
	v_lshlrev_b32_e32 v10, 2, v10
	v_xor_b32_e32 v11, 32, v227
	v_lshlrev_b32_e32 v11, 2, v11
	v_readlane_b32 s48, v253, 26
	v_readlane_b32 s49, v253, 27
	v_readlane_b32 s50, v253, 28
	v_readlane_b32 s51, v253, 29
	v_readlane_b32 s52, v253, 44
	v_readlane_b32 s53, v253, 45
	s_mov_b32 s14, s36
.Lxn_loop:
	s_cmpk_lt_i32 s14, 0x4200
	s_cbranch_scc0 .Lxn_done
	s_mul_i32 s15, s38, 7
	s_add_i32 s15, s15, s14
	s_cmpk_lt_i32 s15, 0x4200
	s_cbranch_scc0 .Lxn_try4
	s_mov_b32 s58, s14
	s_add_i32 s60, s58, 0xffffc000
	s_cmpk_lt_i32 s58, 0x4000
	s_cselect_b32 s54, s48, s50
	s_cselect_b32 s55, s49, s51
	s_cselect_b32 s59, s58, s60
	s_lshl_b32 s59, s59, 12
	s_add_u32 s54, s54, s59
	s_addc_u32 s55, s55, 0
	global_load_dwordx4 v[64:67], v4, s[54:55] nt
	global_load_dwordx4 v[68:71], v4, s[54:55] offset:1024 nt
	global_load_dwordx4 v[72:75], v4, s[54:55] offset:2048 nt
	global_load_dwordx4 v[76:79], v4, s[54:55] offset:3072 nt
	s_add_i32 s58, s58, s38
	s_add_i32 s60, s58, 0xffffc000
	s_cmpk_lt_i32 s58, 0x4000
	s_cselect_b32 s54, s48, s50
	s_cselect_b32 s55, s49, s51
	s_cselect_b32 s59, s58, s60
	s_lshl_b32 s59, s59, 12
	s_add_u32 s54, s54, s59
	s_addc_u32 s55, s55, 0
	global_load_dwordx4 v[80:83], v4, s[54:55] nt
	global_load_dwordx4 v[84:87], v4, s[54:55] offset:1024 nt
	global_load_dwordx4 v[88:91], v4, s[54:55] offset:2048 nt
	global_load_dwordx4 v[92:95], v4, s[54:55] offset:3072 nt
	s_add_i32 s58, s58, s38
	s_add_i32 s60, s58, 0xffffc000
	s_cmpk_lt_i32 s58, 0x4000
	s_cselect_b32 s54, s48, s50
	s_cselect_b32 s55, s49, s51
	s_cselect_b32 s59, s58, s60
	s_lshl_b32 s59, s59, 12
	s_add_u32 s54, s54, s59
	s_addc_u32 s55, s55, 0
	global_load_dwordx4 v[96:99], v4, s[54:55] nt
	global_load_dwordx4 v[100:103], v4, s[54:55] offset:1024 nt
	global_load_dwordx4 v[104:107], v4, s[54:55] offset:2048 nt
	global_load_dwordx4 v[108:111], v4, s[54:55] offset:3072 nt
	s_add_i32 s58, s58, s38
	s_add_i32 s60, s58, 0xffffc000
	s_cmpk_lt_i32 s58, 0x4000
	s_cselect_b32 s54, s48, s50
	s_cselect_b32 s55, s49, s51
	s_cselect_b32 s59, s58, s60
	s_lshl_b32 s59, s59, 12
	s_add_u32 s54, s54, s59
	s_addc_u32 s55, s55, 0
	global_load_dwordx4 v[112:115], v4, s[54:55] nt
	global_load_dwordx4 v[116:119], v4, s[54:55] offset:1024 nt
	global_load_dwordx4 v[120:123], v4, s[54:55] offset:2048 nt
	global_load_dwordx4 v[124:127], v4, s[54:55] offset:3072 nt
	s_add_i32 s58, s58, s38
	s_add_i32 s60, s58, 0xffffc000
	s_cmpk_lt_i32 s58, 0x4000
	s_cselect_b32 s54, s48, s50
	s_cselect_b32 s55, s49, s51
	s_cselect_b32 s59, s58, s60
	s_lshl_b32 s59, s59, 12
	s_add_u32 s54, s54, s59
	s_addc_u32 s55, s55, 0
	global_load_dwordx4 v[128:131], v4, s[54:55] nt
	global_load_dwordx4 v[132:135], v4, s[54:55] offset:1024 nt
	global_load_dwordx4 v[136:139], v4, s[54:55] offset:2048 nt
	global_load_dwordx4 v[140:143], v4, s[54:55] offset:3072 nt
	s_add_i32 s58, s58, s38
	s_add_i32 s60, s58, 0xffffc000
	s_cmpk_lt_i32 s58, 0x4000
	s_cselect_b32 s54, s48, s50
	s_cselect_b32 s55, s49, s51
	s_cselect_b32 s59, s58, s60
	s_lshl_b32 s59, s59, 12
	s_add_u32 s54, s54, s59
	s_addc_u32 s55, s55, 0
	global_load_dwordx4 v[144:147], v4, s[54:55] nt
	global_load_dwordx4 v[148:151], v4, s[54:55] offset:1024 nt
	global_load_dwordx4 v[152:155], v4, s[54:55] offset:2048 nt
	global_load_dwordx4 v[156:159], v4, s[54:55] offset:3072 nt
	s_add_i32 s58, s58, s38
	s_add_i32 s60, s58, 0xffffc000
	s_cmpk_lt_i32 s58, 0x4000
	s_cselect_b32 s54, s48, s50
	s_cselect_b32 s55, s49, s51
	s_cselect_b32 s59, s58, s60
	s_lshl_b32 s59, s59, 12
	s_add_u32 s54, s54, s59
	s_addc_u32 s55, s55, 0
	global_load_dwordx4 v[160:163], v4, s[54:55] nt
	global_load_dwordx4 v[164:167], v4, s[54:55] offset:1024 nt
	global_load_dwordx4 v[168:171], v4, s[54:55] offset:2048 nt
	global_load_dwordx4 v[172:175], v4, s[54:55] offset:3072 nt
	s_add_i32 s58, s58, s38
	s_add_i32 s60, s58, 0xffffc000
	s_cmpk_lt_i32 s58, 0x4000
	s_cselect_b32 s54, s48, s50
	s_cselect_b32 s55, s49, s51
	s_cselect_b32 s59, s58, s60
	s_lshl_b32 s59, s59, 12
	s_add_u32 s54, s54, s59
	s_addc_u32 s55, s55, 0
	global_load_dwordx4 v[176:179], v4, s[54:55] nt
	global_load_dwordx4 v[180:183], v4, s[54:55] offset:1024 nt
	global_load_dwordx4 v[184:187], v4, s[54:55] offset:2048 nt
	global_load_dwordx4 v[188:191], v4, s[54:55] offset:3072 nt
	s_mov_b32 s58, s14
	s_lshl_b32 s59, s58, 11
	s_add_u32 s56, s46, s59
	s_addc_u32 s57, s47, 0
	s_waitcnt vmcnt(28)
	v_pk_mul_f32 v[192:193], v[64:65], v[64:65]
	v_pk_fma_f32 v[192:193], v[66:67], v[66:67], v[192:193]
	v_pk_fma_f32 v[192:193], v[68:69], v[68:69], v[192:193]
	v_pk_fma_f32 v[192:193], v[70:71], v[70:71], v[192:193]
	v_pk_fma_f32 v[192:193], v[72:73], v[72:73], v[192:193]
	v_pk_fma_f32 v[192:193], v[74:75], v[74:75], v[192:193]
	v_pk_fma_f32 v[192:193], v[76:77], v[76:77], v[192:193]
	v_pk_fma_f32 v[192:193], v[78:79], v[78:79], v[192:193]
	v_cvt_pk_bf16_f32 v64, v64, v65
	v_cvt_pk_bf16_f32 v65, v66, v67
	global_store_dwordx2 v5, v[64:65], s[56:57]
	v_cvt_pk_bf16_f32 v68, v68, v69
	v_cvt_pk_bf16_f32 v69, v70, v71
	global_store_dwordx2 v5, v[68:69], s[56:57] offset:512
	v_cvt_pk_bf16_f32 v72, v72, v73
	v_cvt_pk_bf16_f32 v73, v74, v75
	global_store_dwordx2 v5, v[72:73], s[56:57] offset:1024
	v_cvt_pk_bf16_f32 v76, v76, v77
	v_cvt_pk_bf16_f32 v77, v78, v79
	global_store_dwordx2 v5, v[76:77], s[56:57] offset:1536
	v_add_f32_e32 v192, v192, v193
	s_add_i32 s58, s58, s38
	s_lshl_b32 s59, s58, 11
	s_add_u32 s56, s46, s59
	s_addc_u32 s57, s47, 0
	s_waitcnt vmcnt(28)
	v_pk_mul_f32 v[194:195], v[80:81], v[80:81]
	v_pk_fma_f32 v[194:195], v[82:83], v[82:83], v[194:195]
	v_pk_fma_f32 v[194:195], v[84:85], v[84:85], v[194:195]
	v_pk_fma_f32 v[194:195], v[86:87], v[86:87], v[194:195]
	v_pk_fma_f32 v[194:195], v[88:89], v[88:89], v[194:195]
	v_pk_fma_f32 v[194:195], v[90:91], v[90:91], v[194:195]
	v_pk_fma_f32 v[194:195], v[92:93], v[92:93], v[194:195]
	v_pk_fma_f32 v[194:195], v[94:95], v[94:95], v[194:195]
	v_cvt_pk_bf16_f32 v80, v80, v81
	v_cvt_pk_bf16_f32 v81, v82, v83
	global_store_dwordx2 v5, v[80:81], s[56:57]
	v_cvt_pk_bf16_f32 v84, v84, v85
	v_cvt_pk_bf16_f32 v85, v86, v87
	global_store_dwordx2 v5, v[84:85], s[56:57] offset:512
	v_cvt_pk_bf16_f32 v88, v88, v89
	v_cvt_pk_bf16_f32 v89, v90, v91
	global_store_dwordx2 v5, v[88:89], s[56:57] offset:1024
	v_cvt_pk_bf16_f32 v92, v92, v93
	v_cvt_pk_bf16_f32 v93, v94, v95
	global_store_dwordx2 v5, v[92:93], s[56:57] offset:1536
	v_add_f32_e32 v194, v194, v195
	s_add_i32 s58, s58, s38
	s_lshl_b32 s59, s58, 11
	s_add_u32 s56, s46, s59
	s_addc_u32 s57, s47, 0
	s_waitcnt vmcnt(28)
	v_pk_mul_f32 v[196:197], v[96:97], v[96:97]
	v_pk_fma_f32 v[196:197], v[98:99], v[98:99], v[196:197]
	v_pk_fma_f32 v[196:197], v[100:101], v[100:101], v[196:197]
	v_pk_fma_f32 v[196:197], v[102:103], v[102:103], v[196:197]
	v_pk_fma_f32 v[196:197], v[104:105], v[104:105], v[196:197]
	v_pk_fma_f32 v[196:197], v[106:107], v[106:107], v[196:197]
	v_pk_fma_f32 v[196:197], v[108:109], v[108:109], v[196:197]
	v_pk_fma_f32 v[196:197], v[110:111], v[110:111], v[196:197]
	v_cvt_pk_bf16_f32 v96, v96, v97
	v_cvt_pk_bf16_f32 v97, v98, v99
	global_store_dwordx2 v5, v[96:97], s[56:57]
	v_cvt_pk_bf16_f32 v100, v100, v101
	v_cvt_pk_bf16_f32 v101, v102, v103
	global_store_dwordx2 v5, v[100:101], s[56:57] offset:512
	v_cvt_pk_bf16_f32 v104, v104, v105
	v_cvt_pk_bf16_f32 v105, v106, v107
	global_store_dwordx2 v5, v[104:105], s[56:57] offset:1024
	v_cvt_pk_bf16_f32 v108, v108, v109
	v_cvt_pk_bf16_f32 v109, v110, v111
	global_store_dwordx2 v5, v[108:109], s[56:57] offset:1536
	v_add_f32_e32 v196, v196, v197
	s_add_i32 s58, s58, s38
	s_lshl_b32 s59, s58, 11
	s_add_u32 s56, s46, s59
	s_addc_u32 s57, s47, 0
	s_waitcnt vmcnt(28)
	v_pk_mul_f32 v[198:199], v[112:113], v[112:113]
	v_pk_fma_f32 v[198:199], v[114:115], v[114:115], v[198:199]
	v_pk_fma_f32 v[198:199], v[116:117], v[116:117], v[198:199]
	v_pk_fma_f32 v[198:199], v[118:119], v[118:119], v[198:199]
	v_pk_fma_f32 v[198:199], v[120:121], v[120:121], v[198:199]
	v_pk_fma_f32 v[198:199], v[122:123], v[122:123], v[198:199]
	v_pk_fma_f32 v[198:199], v[124:125], v[124:125], v[198:199]
	v_pk_fma_f32 v[198:199], v[126:127], v[126:127], v[198:199]
	v_cvt_pk_bf16_f32 v112, v112, v113
	v_cvt_pk_bf16_f32 v113, v114, v115
	global_store_dwordx2 v5, v[112:113], s[56:57]
	v_cvt_pk_bf16_f32 v116, v116, v117
	v_cvt_pk_bf16_f32 v117, v118, v119
	global_store_dwordx2 v5, v[116:117], s[56:57] offset:512
	v_cvt_pk_bf16_f32 v120, v120, v121
	v_cvt_pk_bf16_f32 v121, v122, v123
	global_store_dwordx2 v5, v[120:121], s[56:57] offset:1024
	v_cvt_pk_bf16_f32 v124, v124, v125
	v_cvt_pk_bf16_f32 v125, v126, v127
	global_store_dwordx2 v5, v[124:125], s[56:57] offset:1536
	v_add_f32_e32 v198, v198, v199
	s_add_i32 s58, s58, s38
	s_lshl_b32 s59, s58, 11
	s_add_u32 s56, s46, s59
	s_addc_u32 s57, s47, 0
	s_waitcnt vmcnt(28)
	v_pk_mul_f32 v[200:201], v[128:129], v[128:129]
	v_pk_fma_f32 v[200:201], v[130:131], v[130:131], v[200:201]
	v_pk_fma_f32 v[200:201], v[132:133], v[132:133], v[200:201]
	v_pk_fma_f32 v[200:201], v[134:135], v[134:135], v[200:201]
	v_pk_fma_f32 v[200:201], v[136:137], v[136:137], v[200:201]
	v_pk_fma_f32 v[200:201], v[138:139], v[138:139], v[200:201]
	v_pk_fma_f32 v[200:201], v[140:141], v[140:141], v[200:201]
	v_pk_fma_f32 v[200:201], v[142:143], v[142:143], v[200:201]
	v_cvt_pk_bf16_f32 v128, v128, v129
	v_cvt_pk_bf16_f32 v129, v130, v131
	global_store_dwordx2 v5, v[128:129], s[56:57]
	v_cvt_pk_bf16_f32 v132, v132, v133
	v_cvt_pk_bf16_f32 v133, v134, v135
	global_store_dwordx2 v5, v[132:133], s[56:57] offset:512
	v_cvt_pk_bf16_f32 v136, v136, v137
	v_cvt_pk_bf16_f32 v137, v138, v139
	global_store_dwordx2 v5, v[136:137], s[56:57] offset:1024
	v_cvt_pk_bf16_f32 v140, v140, v141
	v_cvt_pk_bf16_f32 v141, v142, v143
	global_store_dwordx2 v5, v[140:141], s[56:57] offset:1536
	v_add_f32_e32 v200, v200, v201
	s_add_i32 s58, s58, s38
	s_lshl_b32 s59, s58, 11
	s_add_u32 s56, s46, s59
	s_addc_u32 s57, s47, 0
	s_waitcnt vmcnt(28)
	v_pk_mul_f32 v[202:203], v[144:145], v[144:145]
	v_pk_fma_f32 v[202:203], v[146:147], v[146:147], v[202:203]
	v_pk_fma_f32 v[202:203], v[148:149], v[148:149], v[202:203]
	v_pk_fma_f32 v[202:203], v[150:151], v[150:151], v[202:203]
	v_pk_fma_f32 v[202:203], v[152:153], v[152:153], v[202:203]
	v_pk_fma_f32 v[202:203], v[154:155], v[154:155], v[202:203]
	v_pk_fma_f32 v[202:203], v[156:157], v[156:157], v[202:203]
	v_pk_fma_f32 v[202:203], v[158:159], v[158:159], v[202:203]
	v_cvt_pk_bf16_f32 v144, v144, v145
	v_cvt_pk_bf16_f32 v145, v146, v147
	global_store_dwordx2 v5, v[144:145], s[56:57]
	v_cvt_pk_bf16_f32 v148, v148, v149
	v_cvt_pk_bf16_f32 v149, v150, v151
	global_store_dwordx2 v5, v[148:149], s[56:57] offset:512
	v_cvt_pk_bf16_f32 v152, v152, v153
	v_cvt_pk_bf16_f32 v153, v154, v155
	global_store_dwordx2 v5, v[152:153], s[56:57] offset:1024
	v_cvt_pk_bf16_f32 v156, v156, v157
	v_cvt_pk_bf16_f32 v157, v158, v159
	global_store_dwordx2 v5, v[156:157], s[56:57] offset:1536
	v_add_f32_e32 v202, v202, v203
	s_add_i32 s58, s58, s38
	s_lshl_b32 s59, s58, 11
	s_add_u32 s56, s46, s59
	s_addc_u32 s57, s47, 0
	s_waitcnt vmcnt(28)
	v_pk_mul_f32 v[204:205], v[160:161], v[160:161]
	v_pk_fma_f32 v[204:205], v[162:163], v[162:163], v[204:205]
	v_pk_fma_f32 v[204:205], v[164:165], v[164:165], v[204:205]
	v_pk_fma_f32 v[204:205], v[166:167], v[166:167], v[204:205]
	v_pk_fma_f32 v[204:205], v[168:169], v[168:169], v[204:205]
	v_pk_fma_f32 v[204:205], v[170:171], v[170:171], v[204:205]
	v_pk_fma_f32 v[204:205], v[172:173], v[172:173], v[204:205]
	v_pk_fma_f32 v[204:205], v[174:175], v[174:175], v[204:205]
	v_cvt_pk_bf16_f32 v160, v160, v161
	v_cvt_pk_bf16_f32 v161, v162, v163
	global_store_dwordx2 v5, v[160:161], s[56:57]
	v_cvt_pk_bf16_f32 v164, v164, v165
	v_cvt_pk_bf16_f32 v165, v166, v167
	global_store_dwordx2 v5, v[164:165], s[56:57] offset:512
	v_cvt_pk_bf16_f32 v168, v168, v169
	v_cvt_pk_bf16_f32 v169, v170, v171
	global_store_dwordx2 v5, v[168:169], s[56:57] offset:1024
	v_cvt_pk_bf16_f32 v172, v172, v173
	v_cvt_pk_bf16_f32 v173, v174, v175
	global_store_dwordx2 v5, v[172:173], s[56:57] offset:1536
	v_add_f32_e32 v204, v204, v205
	s_add_i32 s58, s58, s38
	s_lshl_b32 s59, s58, 11
	s_add_u32 s56, s46, s59
	s_addc_u32 s57, s47, 0
	s_waitcnt vmcnt(28)
	v_pk_mul_f32 v[206:207], v[176:177], v[176:177]
	v_pk_fma_f32 v[206:207], v[178:179], v[178:179], v[206:207]
	v_pk_fma_f32 v[206:207], v[180:181], v[180:181], v[206:207]
	v_pk_fma_f32 v[206:207], v[182:183], v[182:183], v[206:207]
	v_pk_fma_f32 v[206:207], v[184:185], v[184:185], v[206:207]
	v_pk_fma_f32 v[206:207], v[186:187], v[186:187], v[206:207]
	v_pk_fma_f32 v[206:207], v[188:189], v[188:189], v[206:207]
	v_pk_fma_f32 v[206:207], v[190:191], v[190:191], v[206:207]
	v_cvt_pk_bf16_f32 v176, v176, v177
	v_cvt_pk_bf16_f32 v177, v178, v179
	global_store_dwordx2 v5, v[176:177], s[56:57]
	v_cvt_pk_bf16_f32 v180, v180, v181
	v_cvt_pk_bf16_f32 v181, v182, v183
	global_store_dwordx2 v5, v[180:181], s[56:57] offset:512
	v_cvt_pk_bf16_f32 v184, v184, v185
	v_cvt_pk_bf16_f32 v185, v186, v187
	global_store_dwordx2 v5, v[184:185], s[56:57] offset:1024
	v_cvt_pk_bf16_f32 v188, v188, v189
	v_cvt_pk_bf16_f32 v189, v190, v191
	global_store_dwordx2 v5, v[188:189], s[56:57] offset:1536
	v_add_f32_e32 v206, v206, v207
	ds_bpermute_b32 v193, v6, v192
	ds_bpermute_b32 v195, v6, v194
	ds_bpermute_b32 v197, v6, v196
	ds_bpermute_b32 v199, v6, v198
	ds_bpermute_b32 v201, v6, v200
	ds_bpermute_b32 v203, v6, v202
	ds_bpermute_b32 v205, v6, v204
	ds_bpermute_b32 v207, v6, v206
	s_waitcnt lgkmcnt(0)
	v_add_f32_e32 v192, v192, v193
	v_add_f32_e32 v194, v194, v195
	v_add_f32_e32 v196, v196, v197
	v_add_f32_e32 v198, v198, v199
	v_add_f32_e32 v200, v200, v201
	v_add_f32_e32 v202, v202, v203
	v_add_f32_e32 v204, v204, v205
	v_add_f32_e32 v206, v206, v207
	ds_bpermute_b32 v193, v7, v192
	ds_bpermute_b32 v195, v7, v194
	ds_bpermute_b32 v197, v7, v196
	ds_bpermute_b32 v199, v7, v198
	ds_bpermute_b32 v201, v7, v200
	ds_bpermute_b32 v203, v7, v202
	ds_bpermute_b32 v205, v7, v204
	ds_bpermute_b32 v207, v7, v206
	s_waitcnt lgkmcnt(0)
	v_add_f32_e32 v192, v192, v193
	v_add_f32_e32 v194, v194, v195
	v_add_f32_e32 v196, v196, v197
	v_add_f32_e32 v198, v198, v199
	v_add_f32_e32 v200, v200, v201
	v_add_f32_e32 v202, v202, v203
	v_add_f32_e32 v204, v204, v205
	v_add_f32_e32 v206, v206, v207
	ds_bpermute_b32 v193, v8, v192
	ds_bpermute_b32 v195, v8, v194
	ds_bpermute_b32 v197, v8, v196
	ds_bpermute_b32 v199, v8, v198
	ds_bpermute_b32 v201, v8, v200
	ds_bpermute_b32 v203, v8, v202
	ds_bpermute_b32 v205, v8, v204
	ds_bpermute_b32 v207, v8, v206
	s_waitcnt lgkmcnt(0)
	v_add_f32_e32 v192, v192, v193
	v_add_f32_e32 v194, v194, v195
	v_add_f32_e32 v196, v196, v197
	v_add_f32_e32 v198, v198, v199
	v_add_f32_e32 v200, v200, v201
	v_add_f32_e32 v202, v202, v203
	v_add_f32_e32 v204, v204, v205
	v_add_f32_e32 v206, v206, v207
	ds_bpermute_b32 v193, v9, v192
	ds_bpermute_b32 v195, v9, v194
	ds_bpermute_b32 v197, v9, v196
	ds_bpermute_b32 v199, v9, v198
	ds_bpermute_b32 v201, v9, v200
	ds_bpermute_b32 v203, v9, v202
	ds_bpermute_b32 v205, v9, v204
	ds_bpermute_b32 v207, v9, v206
	s_waitcnt lgkmcnt(0)
	v_add_f32_e32 v192, v192, v193
	v_add_f32_e32 v194, v194, v195
	v_add_f32_e32 v196, v196, v197
	v_add_f32_e32 v198, v198, v199
	v_add_f32_e32 v200, v200, v201
	v_add_f32_e32 v202, v202, v203
	v_add_f32_e32 v204, v204, v205
	v_add_f32_e32 v206, v206, v207
	ds_bpermute_b32 v193, v10, v192
	ds_bpermute_b32 v195, v10, v194
	ds_bpermute_b32 v197, v10, v196
	ds_bpermute_b32 v199, v10, v198
	ds_bpermute_b32 v201, v10, v200
	ds_bpermute_b32 v203, v10, v202
	ds_bpermute_b32 v205, v10, v204
	ds_bpermute_b32 v207, v10, v206
	s_waitcnt lgkmcnt(0)
	v_add_f32_e32 v192, v192, v193
	v_add_f32_e32 v194, v194, v195
	v_add_f32_e32 v196, v196, v197
	v_add_f32_e32 v198, v198, v199
	v_add_f32_e32 v200, v200, v201
	v_add_f32_e32 v202, v202, v203
	v_add_f32_e32 v204, v204, v205
	v_add_f32_e32 v206, v206, v207
	ds_bpermute_b32 v193, v11, v192
	ds_bpermute_b32 v195, v11, v194
	ds_bpermute_b32 v197, v11, v196
	ds_bpermute_b32 v199, v11, v198
	ds_bpermute_b32 v201, v11, v200
	ds_bpermute_b32 v203, v11, v202
	ds_bpermute_b32 v205, v11, v204
	ds_bpermute_b32 v207, v11, v206
	s_waitcnt lgkmcnt(0)
	v_add_f32_e32 v192, v192, v193
	v_add_f32_e32 v194, v194, v195
	v_add_f32_e32 v196, v196, v197
	v_add_f32_e32 v198, v198, v199
	v_add_f32_e32 v200, v200, v201
	v_add_f32_e32 v202, v202, v203
	v_add_f32_e32 v204, v204, v205
	v_add_f32_e32 v206, v206, v207
	s_mov_b64 exec, 1
	s_mov_b32 s58, s14
	s_lshl_b32 s59, s58, 2
	s_add_u32 s56, s52, s59
	s_addc_u32 s57, s53, 0
	global_store_dword v12, v192, s[56:57]
	s_add_i32 s58, s58, s38
	s_lshl_b32 s59, s58, 2
	s_add_u32 s56, s52, s59
	s_addc_u32 s57, s53, 0
	global_store_dword v12, v194, s[56:57]
	s_add_i32 s58, s58, s38
	s_lshl_b32 s59, s58, 2
	s_add_u32 s56, s52, s59
	s_addc_u32 s57, s53, 0
	global_store_dword v12, v196, s[56:57]
	s_add_i32 s58, s58, s38
	s_lshl_b32 s59, s58, 2
	s_add_u32 s56, s52, s59
	s_addc_u32 s57, s53, 0
	global_store_dword v12, v198, s[56:57]
	s_add_i32 s58, s58, s38
	s_lshl_b32 s59, s58, 2
	s_add_u32 s56, s52, s59
	s_addc_u32 s57, s53, 0
	global_store_dword v12, v200, s[56:57]
	s_add_i32 s58, s58, s38
	s_lshl_b32 s59, s58, 2
	s_add_u32 s56, s52, s59
	s_addc_u32 s57, s53, 0
	global_store_dword v12, v202, s[56:57]
	s_add_i32 s58, s58, s38
	s_lshl_b32 s59, s58, 2
	s_add_u32 s56, s52, s59
	s_addc_u32 s57, s53, 0
	global_store_dword v12, v204, s[56:57]
	s_add_i32 s58, s58, s38
	s_lshl_b32 s59, s58, 2
	s_add_u32 s56, s52, s59
	s_addc_u32 s57, s53, 0
	global_store_dword v12, v206, s[56:57]
	s_mov_b64 exec, -1
	s_lshl_b32 s15, s38, 3
	s_add_i32 s14, s14, s15
	s_branch .Lxn_loop
.Lxn_try4:
	s_mul_i32 s15, s38, 3
	s_add_i32 s15, s15, s14
	s_cmpk_lt_i32 s15, 0x4200
	s_cbranch_scc0 .Lxn_one
	s_mov_b32 s58, s14
	s_add_i32 s60, s58, 0xffffc000
	s_cmpk_lt_i32 s58, 0x4000
	s_cselect_b32 s54, s48, s50
	s_cselect_b32 s55, s49, s51
	s_cselect_b32 s59, s58, s60
	s_lshl_b32 s59, s59, 12
	s_add_u32 s54, s54, s59
	s_addc_u32 s55, s55, 0
	global_load_dwordx4 v[64:67], v4, s[54:55] nt
	global_load_dwordx4 v[68:71], v4, s[54:55] offset:1024 nt
	global_load_dwordx4 v[72:75], v4, s[54:55] offset:2048 nt
	global_load_dwordx4 v[76:79], v4, s[54:55] offset:3072 nt
	s_add_i32 s58, s58, s38
	s_add_i32 s60, s58, 0xffffc000
	s_cmpk_lt_i32 s58, 0x4000
	s_cselect_b32 s54, s48, s50
	s_cselect_b32 s55, s49, s51
	s_cselect_b32 s59, s58, s60
	s_lshl_b32 s59, s59, 12
	s_add_u32 s54, s54, s59
	s_addc_u32 s55, s55, 0
	global_load_dwordx4 v[80:83], v4, s[54:55] nt
	global_load_dwordx4 v[84:87], v4, s[54:55] offset:1024 nt
	global_load_dwordx4 v[88:91], v4, s[54:55] offset:2048 nt
	global_load_dwordx4 v[92:95], v4, s[54:55] offset:3072 nt
	s_add_i32 s58, s58, s38
	s_add_i32 s60, s58, 0xffffc000
	s_cmpk_lt_i32 s58, 0x4000
	s_cselect_b32 s54, s48, s50
	s_cselect_b32 s55, s49, s51
	s_cselect_b32 s59, s58, s60
	s_lshl_b32 s59, s59, 12
	s_add_u32 s54, s54, s59
	s_addc_u32 s55, s55, 0
	global_load_dwordx4 v[96:99], v4, s[54:55] nt
	global_load_dwordx4 v[100:103], v4, s[54:55] offset:1024 nt
	global_load_dwordx4 v[104:107], v4, s[54:55] offset:2048 nt
	global_load_dwordx4 v[108:111], v4, s[54:55] offset:3072 nt
	s_add_i32 s58, s58, s38
	s_add_i32 s60, s58, 0xffffc000
	s_cmpk_lt_i32 s58, 0x4000
	s_cselect_b32 s54, s48, s50
	s_cselect_b32 s55, s49, s51
	s_cselect_b32 s59, s58, s60
	s_lshl_b32 s59, s59, 12
	s_add_u32 s54, s54, s59
	s_addc_u32 s55, s55, 0
	global_load_dwordx4 v[112:115], v4, s[54:55] nt
	global_load_dwordx4 v[116:119], v4, s[54:55] offset:1024 nt
	global_load_dwordx4 v[120:123], v4, s[54:55] offset:2048 nt
	global_load_dwordx4 v[124:127], v4, s[54:55] offset:3072 nt
	s_mov_b32 s58, s14
	s_lshl_b32 s59, s58, 11
	s_add_u32 s56, s46, s59
	s_addc_u32 s57, s47, 0
	s_waitcnt vmcnt(12)
	v_pk_mul_f32 v[192:193], v[64:65], v[64:65]
	v_pk_fma_f32 v[192:193], v[66:67], v[66:67], v[192:193]
	v_pk_fma_f32 v[192:193], v[68:69], v[68:69], v[192:193]
	v_pk_fma_f32 v[192:193], v[70:71], v[70:71], v[192:193]
	v_pk_fma_f32 v[192:193], v[72:73], v[72:73], v[192:193]
	v_pk_fma_f32 v[192:193], v[74:75], v[74:75], v[192:193]
	v_pk_fma_f32 v[192:193], v[76:77], v[76:77], v[192:193]
	v_pk_fma_f32 v[192:193], v[78:79], v[78:79], v[192:193]
	v_cvt_pk_bf16_f32 v64, v64, v65
	v_cvt_pk_bf16_f32 v65, v66, v67
	global_store_dwordx2 v5, v[64:65], s[56:57]
	v_cvt_pk_bf16_f32 v68, v68, v69
	v_cvt_pk_bf16_f32 v69, v70, v71
	global_store_dwordx2 v5, v[68:69], s[56:57] offset:512
	v_cvt_pk_bf16_f32 v72, v72, v73
	v_cvt_pk_bf16_f32 v73, v74, v75
	global_store_dwordx2 v5, v[72:73], s[56:57] offset:1024
	v_cvt_pk_bf16_f32 v76, v76, v77
	v_cvt_pk_bf16_f32 v77, v78, v79
	global_store_dwordx2 v5, v[76:77], s[56:57] offset:1536
	v_add_f32_e32 v192, v192, v193
	s_add_i32 s58, s58, s38
	s_lshl_b32 s59, s58, 11
	s_add_u32 s56, s46, s59
	s_addc_u32 s57, s47, 0
	s_waitcnt vmcnt(12)
	v_pk_mul_f32 v[194:195], v[80:81], v[80:81]
	v_pk_fma_f32 v[194:195], v[82:83], v[82:83], v[194:195]
	v_pk_fma_f32 v[194:195], v[84:85], v[84:85], v[194:195]
	v_pk_fma_f32 v[194:195], v[86:87], v[86:87], v[194:195]
	v_pk_fma_f32 v[194:195], v[88:89], v[88:89], v[194:195]
	v_pk_fma_f32 v[194:195], v[90:91], v[90:91], v[194:195]
	v_pk_fma_f32 v[194:195], v[92:93], v[92:93], v[194:195]
	v_pk_fma_f32 v[194:195], v[94:95], v[94:95], v[194:195]
	v_cvt_pk_bf16_f32 v80, v80, v81
	v_cvt_pk_bf16_f32 v81, v82, v83
	global_store_dwordx2 v5, v[80:81], s[56:57]
	v_cvt_pk_bf16_f32 v84, v84, v85
	v_cvt_pk_bf16_f32 v85, v86, v87
	global_store_dwordx2 v5, v[84:85], s[56:57] offset:512
	v_cvt_pk_bf16_f32 v88, v88, v89
	v_cvt_pk_bf16_f32 v89, v90, v91
	global_store_dwordx2 v5, v[88:89], s[56:57] offset:1024
	v_cvt_pk_bf16_f32 v92, v92, v93
	v_cvt_pk_bf16_f32 v93, v94, v95
	global_store_dwordx2 v5, v[92:93], s[56:57] offset:1536
	v_add_f32_e32 v194, v194, v195
	s_add_i32 s58, s58, s38
	s_lshl_b32 s59, s58, 11
	s_add_u32 s56, s46, s59
	s_addc_u32 s57, s47, 0
	s_waitcnt vmcnt(12)
	v_pk_mul_f32 v[196:197], v[96:97], v[96:97]
	v_pk_fma_f32 v[196:197], v[98:99], v[98:99], v[196:197]
	v_pk_fma_f32 v[196:197], v[100:101], v[100:101], v[196:197]
	v_pk_fma_f32 v[196:197], v[102:103], v[102:103], v[196:197]
	v_pk_fma_f32 v[196:197], v[104:105], v[104:105], v[196:197]
	v_pk_fma_f32 v[196:197], v[106:107], v[106:107], v[196:197]
	v_pk_fma_f32 v[196:197], v[108:109], v[108:109], v[196:197]
	v_pk_fma_f32 v[196:197], v[110:111], v[110:111], v[196:197]
	v_cvt_pk_bf16_f32 v96, v96, v97
	v_cvt_pk_bf16_f32 v97, v98, v99
	global_store_dwordx2 v5, v[96:97], s[56:57]
	v_cvt_pk_bf16_f32 v100, v100, v101
	v_cvt_pk_bf16_f32 v101, v102, v103
	global_store_dwordx2 v5, v[100:101], s[56:57] offset:512
	v_cvt_pk_bf16_f32 v104, v104, v105
	v_cvt_pk_bf16_f32 v105, v106, v107
	global_store_dwordx2 v5, v[104:105], s[56:57] offset:1024
	v_cvt_pk_bf16_f32 v108, v108, v109
	v_cvt_pk_bf16_f32 v109, v110, v111
	global_store_dwordx2 v5, v[108:109], s[56:57] offset:1536
	v_add_f32_e32 v196, v196, v197
	s_add_i32 s58, s58, s38
	s_lshl_b32 s59, s58, 11
	s_add_u32 s56, s46, s59
	s_addc_u32 s57, s47, 0
	s_waitcnt vmcnt(12)
	v_pk_mul_f32 v[198:199], v[112:113], v[112:113]
	v_pk_fma_f32 v[198:199], v[114:115], v[114:115], v[198:199]
	v_pk_fma_f32 v[198:199], v[116:117], v[116:117], v[198:199]
	v_pk_fma_f32 v[198:199], v[118:119], v[118:119], v[198:199]
	v_pk_fma_f32 v[198:199], v[120:121], v[120:121], v[198:199]
	v_pk_fma_f32 v[198:199], v[122:123], v[122:123], v[198:199]
	v_pk_fma_f32 v[198:199], v[124:125], v[124:125], v[198:199]
	v_pk_fma_f32 v[198:199], v[126:127], v[126:127], v[198:199]
	v_cvt_pk_bf16_f32 v112, v112, v113
	v_cvt_pk_bf16_f32 v113, v114, v115
	global_store_dwordx2 v5, v[112:113], s[56:57]
	v_cvt_pk_bf16_f32 v116, v116, v117
	v_cvt_pk_bf16_f32 v117, v118, v119
	global_store_dwordx2 v5, v[116:117], s[56:57] offset:512
	v_cvt_pk_bf16_f32 v120, v120, v121
	v_cvt_pk_bf16_f32 v121, v122, v123
	global_store_dwordx2 v5, v[120:121], s[56:57] offset:1024
	v_cvt_pk_bf16_f32 v124, v124, v125
	v_cvt_pk_bf16_f32 v125, v126, v127
	global_store_dwordx2 v5, v[124:125], s[56:57] offset:1536
	v_add_f32_e32 v198, v198, v199
	ds_bpermute_b32 v193, v6, v192
	ds_bpermute_b32 v195, v6, v194
	ds_bpermute_b32 v197, v6, v196
	ds_bpermute_b32 v199, v6, v198
	s_waitcnt lgkmcnt(0)
	v_add_f32_e32 v192, v192, v193
	v_add_f32_e32 v194, v194, v195
	v_add_f32_e32 v196, v196, v197
	v_add_f32_e32 v198, v198, v199
	ds_bpermute_b32 v193, v7, v192
	ds_bpermute_b32 v195, v7, v194
	ds_bpermute_b32 v197, v7, v196
	ds_bpermute_b32 v199, v7, v198
	s_waitcnt lgkmcnt(0)
	v_add_f32_e32 v192, v192, v193
	v_add_f32_e32 v194, v194, v195
	v_add_f32_e32 v196, v196, v197
	v_add_f32_e32 v198, v198, v199
	ds_bpermute_b32 v193, v8, v192
	ds_bpermute_b32 v195, v8, v194
	ds_bpermute_b32 v197, v8, v196
	ds_bpermute_b32 v199, v8, v198
	s_waitcnt lgkmcnt(0)
	v_add_f32_e32 v192, v192, v193
	v_add_f32_e32 v194, v194, v195
	v_add_f32_e32 v196, v196, v197
	v_add_f32_e32 v198, v198, v199
	ds_bpermute_b32 v193, v9, v192
	ds_bpermute_b32 v195, v9, v194
	ds_bpermute_b32 v197, v9, v196
	ds_bpermute_b32 v199, v9, v198
	s_waitcnt lgkmcnt(0)
	v_add_f32_e32 v192, v192, v193
	v_add_f32_e32 v194, v194, v195
	v_add_f32_e32 v196, v196, v197
	v_add_f32_e32 v198, v198, v199
	ds_bpermute_b32 v193, v10, v192
	ds_bpermute_b32 v195, v10, v194
	ds_bpermute_b32 v197, v10, v196
	ds_bpermute_b32 v199, v10, v198
	s_waitcnt lgkmcnt(0)
	v_add_f32_e32 v192, v192, v193
	v_add_f32_e32 v194, v194, v195
	v_add_f32_e32 v196, v196, v197
	v_add_f32_e32 v198, v198, v199
	ds_bpermute_b32 v193, v11, v192
	ds_bpermute_b32 v195, v11, v194
	ds_bpermute_b32 v197, v11, v196
	ds_bpermute_b32 v199, v11, v198
	s_waitcnt lgkmcnt(0)
	v_add_f32_e32 v192, v192, v193
	v_add_f32_e32 v194, v194, v195
	v_add_f32_e32 v196, v196, v197
	v_add_f32_e32 v198, v198, v199
	s_mov_b64 exec, 1
	s_mov_b32 s58, s14
	s_lshl_b32 s59, s58, 2
	s_add_u32 s56, s52, s59
	s_addc_u32 s57, s53, 0
	global_store_dword v12, v192, s[56:57]
	s_add_i32 s58, s58, s38
	s_lshl_b32 s59, s58, 2
	s_add_u32 s56, s52, s59
	s_addc_u32 s57, s53, 0
	global_store_dword v12, v194, s[56:57]
	s_add_i32 s58, s58, s38
	s_lshl_b32 s59, s58, 2
	s_add_u32 s56, s52, s59
	s_addc_u32 s57, s53, 0
	global_store_dword v12, v196, s[56:57]
	s_add_i32 s58, s58, s38
	s_lshl_b32 s59, s58, 2
	s_add_u32 s56, s52, s59
	s_addc_u32 s57, s53, 0
	global_store_dword v12, v198, s[56:57]
	s_mov_b64 exec, -1
	s_lshl_b32 s15, s38, 2
	s_add_i32 s14, s14, s15
	s_branch .Lxn_loop
.Lxn_one:
	s_mov_b32 s58, s14
	s_add_i32 s60, s58, 0xffffc000
	s_cmpk_lt_i32 s58, 0x4000
	s_cselect_b32 s54, s48, s50
	s_cselect_b32 s55, s49, s51
	s_cselect_b32 s59, s58, s60
	s_lshl_b32 s59, s59, 12
	s_add_u32 s54, s54, s59
	s_addc_u32 s55, s55, 0
	global_load_dwordx4 v[64:67], v4, s[54:55] nt
	global_load_dwordx4 v[68:71], v4, s[54:55] offset:1024 nt
	global_load_dwordx4 v[72:75], v4, s[54:55] offset:2048 nt
	global_load_dwordx4 v[76:79], v4, s[54:55] offset:3072 nt
	s_mov_b32 s58, s14
	s_lshl_b32 s59, s58, 11
	s_add_u32 s56, s46, s59
	s_addc_u32 s57, s47, 0
	s_waitcnt vmcnt(0)
	v_pk_mul_f32 v[192:193], v[64:65], v[64:65]
	v_pk_fma_f32 v[192:193], v[66:67], v[66:67], v[192:193]
	v_pk_fma_f32 v[192:193], v[68:69], v[68:69], v[192:193]
	v_pk_fma_f32 v[192:193], v[70:71], v[70:71], v[192:193]
	v_pk_fma_f32 v[192:193], v[72:73], v[72:73], v[192:193]
	v_pk_fma_f32 v[192:193], v[74:75], v[74:75], v[192:193]
	v_pk_fma_f32 v[192:193], v[76:77], v[76:77], v[192:193]
	v_pk_fma_f32 v[192:193], v[78:79], v[78:79], v[192:193]
	v_cvt_pk_bf16_f32 v64, v64, v65
	v_cvt_pk_bf16_f32 v65, v66, v67
	global_store_dwordx2 v5, v[64:65], s[56:57]
	v_cvt_pk_bf16_f32 v68, v68, v69
	v_cvt_pk_bf16_f32 v69, v70, v71
	global_store_dwordx2 v5, v[68:69], s[56:57] offset:512
	v_cvt_pk_bf16_f32 v72, v72, v73
	v_cvt_pk_bf16_f32 v73, v74, v75
	global_store_dwordx2 v5, v[72:73], s[56:57] offset:1024
	v_cvt_pk_bf16_f32 v76, v76, v77
	v_cvt_pk_bf16_f32 v77, v78, v79
	global_store_dwordx2 v5, v[76:77], s[56:57] offset:1536
	v_add_f32_e32 v192, v192, v193
	ds_bpermute_b32 v193, v6, v192
	s_waitcnt lgkmcnt(0)
	v_add_f32_e32 v192, v192, v193
	ds_bpermute_b32 v193, v7, v192
	s_waitcnt lgkmcnt(0)
	v_add_f32_e32 v192, v192, v193
	ds_bpermute_b32 v193, v8, v192
	s_waitcnt lgkmcnt(0)
	v_add_f32_e32 v192, v192, v193
	ds_bpermute_b32 v193, v9, v192
	s_waitcnt lgkmcnt(0)
	v_add_f32_e32 v192, v192, v193
	ds_bpermute_b32 v193, v10, v192
	s_waitcnt lgkmcnt(0)
	v_add_f32_e32 v192, v192, v193
	ds_bpermute_b32 v193, v11, v192
	s_waitcnt lgkmcnt(0)
	v_add_f32_e32 v192, v192, v193
	s_mov_b64 exec, 1
	s_mov_b32 s58, s14
	s_lshl_b32 s59, s58, 2
	s_add_u32 s56, s52, s59
	s_addc_u32 s57, s53, 0
	global_store_dword v12, v192, s[56:57]
	s_mov_b64 exec, -1
	s_add_i32 s14, s14, s38
	s_branch .Lxn_loop
.Lxn_done:
.LBB0_192:
	v_readlane_b32 s8, v253, 0
	v_readlane_b32 s10, v253, 2
	v_readlane_b32 s11, v253, 3
	s_cmp_lg_u64 s[10:11], 0
	v_readlane_b32 s9, v253, 1
	s_cbranch_scc1 .LBB0_204
	v_lshrrev_b32_e32 v1, 20, v0
	v_lshrrev_b32_e32 v0, 10, v0
	v_or_b32_e32 v0, v0, v1
	s_movk_i32 s0, 0x3ff
	v_and_or_b32 v0, v0, s0, v226
	v_cmp_eq_u32_e32 vcc, 0, v0
	s_waitcnt lgkmcnt(0)
	s_barrier
	s_and_saveexec_b64 s[0:1], vcc
	s_cbranch_execz .LBB0_203
	buffer_wbl2 sc1
	s_waitcnt vmcnt(0)
	s_load_dwordx2 s[4:5], s[6:7], 0x58
	v_mov_b32_e32 v2, 0
	s_mov_b64 s[10:11], exec
	v_mbcnt_lo_u32_b32 v1, s10, 0
	v_mbcnt_hi_u32_b32 v1, s11, v1
	s_waitcnt lgkmcnt(0)
	global_load_dword v0, v2, s[4:5] offset:40
	v_cmp_eq_u32_e32 vcc, 0, v1
	s_and_saveexec_b64 s[6:7], vcc
	s_cbranch_execz .LBB0_196
	s_bcnt1_i32_b64 s8, s[10:11]
	v_mov_b32_e32 v3, s8
	global_atomic_add v3, v2, v3, s[4:5] offset:32 sc0

.LBB0_946:
	v_readfirstlane_b32 s4, v226
	s_lshr_b32 s4, s4, 6
	s_lshl_b32 s5, s2, 3
	s_add_i32 s14, s4, s5
	s_lshl_b32 s38, s78, 3
	v_readlane_b32 s48, v253, 0
	v_readlane_b32 s49, v253, 1
	v_readlane_b32 s50, v253, 2
	v_readlane_b32 s51, v253, 3
	v_readlane_b32 s54, v253, 24
	v_readlane_b32 s55, v253, 25
	s_add_u32 s52, s50, 0x342000
	s_addc_u32 s53, s51, 0
	v_lshlrev_b32_e32 v4, 4, v227
	v_lshlrev_b32_e32 v5, 5, v227
	v_mov_b32_e32 v24, 0x358637bd
	global_load_dwordx4 v[8:11], v5, s[54:55]
	global_load_dwordx4 v[12:15], v5, s[54:55] offset:16
	global_load_dwordx4 v[16:19], v5, s[54:55] offset:2048
	global_load_dwordx4 v[20:23], v5, s[54:55] offset:2064
.Lfn_loop:
	s_cmpk_lt_i32 s14, 0x4200
	s_cbranch_scc0 .LBB0_955
	s_mul_i32 s15, s38, 7
	s_add_i32 s15, s15, s14
	s_cmpk_lt_i32 s15, 0x4200
	s_cbranch_scc0 .Lfn_try4
	s_mov_b32 s58, s14
	s_lshl_b32 s59, s58, 11
	s_add_u32 s56, s46, s59
	s_addc_u32 s57, s47, 0
	s_lshl_b32 s59, s58, 2
	s_load_dword s60, s[52:53], s59
	global_load_dwordx4 v[32:35], v4, s[56:57]
	global_load_dwordx4 v[36:39], v4, s[56:57] offset:1024
	s_add_i32 s58, s58, s38
	s_lshl_b32 s59, s58, 11
	s_add_u32 s56, s46, s59
	s_addc_u32 s57, s47, 0
	s_lshl_b32 s59, s58, 2
	s_load_dword s61, s[52:53], s59
	global_load_dwordx4 v[40:43], v4, s[56:57]
	global_load_dwordx4 v[44:47], v4, s[56:57] offset:1024
	s_add_i32 s58, s58, s38
	s_lshl_b32 s59, s58, 11
	s_add_u32 s56, s46, s59
	s_addc_u32 s57, s47, 0
	s_lshl_b32 s59, s58, 2
	s_load_dword s62, s[52:53], s59
	global_load_dwordx4 v[48:51], v4, s[56:57]
	global_load_dwordx4 v[52:55], v4, s[56:57] offset:1024
	s_add_i32 s58, s58, s38
	s_lshl_b32 s59, s58, 11
	s_add_u32 s56, s46, s59
	s_addc_u32 s57, s47, 0
	s_lshl_b32 s59, s58, 2
	s_load_dword s63, s[52:53], s59
	global_load_dwordx4 v[56:59], v4, s[56:57]
	global_load_dwordx4 v[60:63], v4, s[56:57] offset:1024
	s_add_i32 s58, s58, s38
	s_lshl_b32 s59, s58, 11
	s_add_u32 s56, s46, s59
	s_addc_u32 s57, s47, 0
	s_lshl_b32 s59, s58, 2
	s_load_dword s64, s[52:53], s59
	global_load_dwordx4 v[64:67], v4, s[56:57]
	global_load_dwordx4 v[68:71], v4, s[56:57] offset:1024
	s_add_i32 s58, s58, s38
	s_lshl_b32 s59, s58, 11
	s_add_u32 s56, s46, s59
	s_addc_u32 s57, s47, 0
	s_lshl_b32 s59, s58, 2
	s_load_dword s65, s[52:53], s59
	global_load_dwordx4 v[72:75], v4, s[56:57]
	global_load_dwordx4 v[76:79], v4, s[56:57] offset:1024
	s_add_i32 s58, s58, s38
	s_lshl_b32 s59, s58, 11
	s_add_u32 s56, s46, s59
	s_addc_u32 s57, s47, 0
	s_lshl_b32 s59, s58, 2
	s_load_dword s66, s[52:53], s59
	global_load_dwordx4 v[80:83], v4, s[56:57]
	global_load_dwordx4 v[84:87], v4, s[56:57] offset:1024
	s_add_i32 s58, s58, s38
	s_lshl_b32 s59, s58, 11
	s_add_u32 s56, s46, s59
	s_addc_u32 s57, s47, 0
	s_lshl_b32 s59, s58, 2
	s_load_dword s67, s[52:53], s59
	global_load_dwordx4 v[88:91], v4, s[56:57]
	global_load_dwordx4 v[92:95], v4, s[56:57] offset:1024
	s_waitcnt lgkmcnt(0)
	s_mov_b32 s58, s14
	s_lshl_b32 s59, s58, 12
	s_add_u32 s56, s48, s59
	s_addc_u32 s57, s49, 0
	v_mov_b32_e32 v6, s60
	v_fmamk_f32 v6, v6, 0x3a800000, v24
	v_rsq_f32_e32 v6, v6
	s_waitcnt vmcnt(14)
	v_lshlrev_b32_e32 v96, 16, v32
	v_and_b32_e32 v97, 0xffff0000, v32
	v_lshlrev_b32_e32 v98, 16, v33
	v_and_b32_e32 v99, 0xffff0000, v33
	v_lshlrev_b32_e32 v100, 16, v34
	v_and_b32_e32 v101, 0xffff0000, v34
	v_lshlrev_b32_e32 v102, 16, v35
	v_and_b32_e32 v103, 0xffff0000, v35
	v_lshlrev_b32_e32 v104, 16, v36
	v_and_b32_e32 v105, 0xffff0000, v36
	v_lshlrev_b32_e32 v106, 16, v37
	v_and_b32_e32 v107, 0xffff0000, v37
	v_lshlrev_b32_e32 v108, 16, v38
	v_and_b32_e32 v109, 0xffff0000, v38
	v_lshlrev_b32_e32 v110, 16, v39
	v_and_b32_e32 v111, 0xffff0000, v39
	v_pk_mul_f32 v[96:97], v[6:7], v[96:97] op_sel_hi:[0,1]
	v_pk_mul_f32 v[98:99], v[6:7], v[98:99] op_sel_hi:[0,1]
	v_pk_mul_f32 v[100:101], v[6:7], v[100:101] op_sel_hi:[0,1]
	v_pk_mul_f32 v[102:103], v[6:7], v[102:103] op_sel_hi:[0,1]
	v_pk_mul_f32 v[104:105], v[6:7], v[104:105] op_sel_hi:[0,1]
	v_pk_mul_f32 v[106:107], v[6:7], v[106:107] op_sel_hi:[0,1]
	v_pk_mul_f32 v[108:109], v[6:7], v[108:109] op_sel_hi:[0,1]
	v_pk_mul_f32 v[110:111], v[6:7], v[110:111] op_sel_hi:[0,1]
	v_pk_mul_f32 v[96:97], v[8:9], v[96:97]
	v_pk_mul_f32 v[98:99], v[10:11], v[98:99]
	v_pk_mul_f32 v[100:101], v[12:13], v[100:101]
	v_pk_mul_f32 v[102:103], v[14:15], v[102:103]
	v_pk_mul_f32 v[104:105], v[16:17], v[104:105]
	v_pk_mul_f32 v[106:107], v[18:19], v[106:107]
	v_pk_mul_f32 v[108:109], v[20:21], v[108:109]
	v_pk_mul_f32 v[110:111], v[22:23], v[110:111]
	global_store_dwordx4 v5, v[96:99], s[56:57] nt
	global_store_dwordx4 v5, v[100:103], s[56:57] offset:16 nt
	global_store_dwordx4 v5, v[104:107], s[56:57] offset:2048 nt
	global_store_dwordx4 v5, v[108:111], s[56:57] offset:2064 nt
	s_add_i32 s58, s58, s38
	s_lshl_b32 s59, s58, 12
	s_add_u32 s56, s48, s59
	s_addc_u32 s57, s49, 0
	v_mov_b32_e32 v6, s61
	v_fmamk_f32 v6, v6, 0x3a800000, v24
	v_rsq_f32_e32 v6, v6
	s_waitcnt vmcnt(16)
	v_lshlrev_b32_e32 v112, 16, v40
	v_and_b32_e32 v113, 0xffff0000, v40
	v_lshlrev_b32_e32 v114, 16, v41
	v_and_b32_e32 v115, 0xffff0000, v41
	v_lshlrev_b32_e32 v116, 16, v42
	v_and_b32_e32 v117, 0xffff0000, v42
	v_lshlrev_b32_e32 v118, 16, v43
	v_and_b32_e32 v119, 0xffff0000, v43
	v_lshlrev_b32_e32 v120, 16, v44
	v_and_b32_e32 v121, 0xffff0000, v44
	v_lshlrev_b32_e32 v122, 16, v45
	v_and_b32_e32 v123, 0xffff0000, v45
	v_lshlrev_b32_e32 v124, 16, v46
	v_and_b32_e32 v125, 0xffff0000, v46
	v_lshlrev_b32_e32 v126, 16, v47
	v_and_b32_e32 v127, 0xffff0000, v47
	v_pk_mul_f32 v[112:113], v[6:7], v[112:113] op_sel_hi:[0,1]
	v_pk_mul_f32 v[114:115], v[6:7], v[114:115] op_sel_hi:[0,1]
	v_pk_mul_f32 v[116:117], v[6:7], v[116:117] op_sel_hi:[0,1]
	v_pk_mul_f32 v[118:119], v[6:7], v[118:119] op_sel_hi:[0,1]
	v_pk_mul_f32 v[120:121], v[6:7], v[120:121] op_sel_hi:[0,1]
	v_pk_mul_f32 v[122:123], v[6:7], v[122:123] op_sel_hi:[0,1]
	v_pk_mul_f32 v[124:125], v[6:7], v[124:125] op_sel_hi:[0,1]
	v_pk_mul_f32 v[126:127], v[6:7], v[126:127] op_sel_hi:[0,1]
	v_pk_mul_f32 v[112:113], v[8:9], v[112:113]
	v_pk_mul_f32 v[114:115], v[10:11], v[114:115]
	v_pk_mul_f32 v[116:117], v[12:13], v[116:117]
	v_pk_mul_f32 v[118:119], v[14:15], v[118:119]
	v_pk_mul_f32 v[120:121], v[16:17], v[120:121]
	v_pk_mul_f32 v[122:123], v[18:19], v[122:123]
	v_pk_mul_f32 v[124:125], v[20:21], v[124:125]
	v_pk_mul_f32 v[126:127], v[22:23], v[126:127]
	global_store_dwordx4 v5, v[112:115], s[56:57] nt
	global_store_dwordx4 v5, v[116:119], s[56:57] offset:16 nt
	global_store_dwordx4 v5, v[120:123], s[56:57] offset:2048 nt
	global_store_dwordx4 v5, v[124:127], s[56:57] offset:2064 nt
	s_add_i32 s58, s58, s38
	s_lshl_b32 s59, s58, 12
	s_add_u32 s56, s48, s59
	s_addc_u32 s57, s49, 0
	v_mov_b32_e32 v6, s62
	v_fmamk_f32 v6, v6, 0x3a800000, v24
	v_rsq_f32_e32 v6, v6
	s_waitcnt vmcnt(18)
	v_lshlrev_b32_e32 v128, 16, v48
	v_and_b32_e32 v129, 0xffff0000, v48
	v_lshlrev_b32_e32 v130, 16, v49
	v_and_b32_e32 v131, 0xffff0000, v49
	v_lshlrev_b32_e32 v132, 16, v50
	v_and_b32_e32 v133, 0xffff0000, v50
	v_lshlrev_b32_e32 v134, 16, v51
	v_and_b32_e32 v135, 0xffff0000, v51
	v_lshlrev_b32_e32 v136, 16, v52
	v_and_b32_e32 v137, 0xffff0000, v52
	v_lshlrev_b32_e32 v138, 16, v53
	v_and_b32_e32 v139, 0xffff0000, v53
	v_lshlrev_b32_e32 v140, 16, v54
	v_and_b32_e32 v141, 0xffff0000, v54
	v_lshlrev_b32_e32 v142, 16, v55
	v_and_b32_e32 v143, 0xffff0000, v55
	v_pk_mul_f32 v[128:129], v[6:7], v[128:129] op_sel_hi:[0,1]
	v_pk_mul_f32 v[130:131], v[6:7], v[130:131] op_sel_hi:[0,1]
	v_pk_mul_f32 v[132:133], v[6:7], v[132:133] op_sel_hi:[0,1]
	v_pk_mul_f32 v[134:135], v[6:7], v[134:135] op_sel_hi:[0,1]
	v_pk_mul_f32 v[136:137], v[6:7], v[136:137] op_sel_hi:[0,1]
	v_pk_mul_f32 v[138:139], v[6:7], v[138:139] op_sel_hi:[0,1]
	v_pk_mul_f32 v[140:141], v[6:7], v[140:141] op_sel_hi:[0,1]
	v_pk_mul_f32 v[142:143], v[6:7], v[142:143] op_sel_hi:[0,1]
	v_pk_mul_f32 v[128:129], v[8:9], v[128:129]
	v_pk_mul_f32 v[130:131], v[10:11], v[130:131]
	v_pk_mul_f32 v[132:133], v[12:13], v[132:133]
	v_pk_mul_f32 v[134:135], v[14:15], v[134:135]
	v_pk_mul_f32 v[136:137], v[16:17], v[136:137]
	v_pk_mul_f32 v[138:139], v[18:19], v[138:139]
	v_pk_mul_f32 v[140:141], v[20:21], v[140:141]
	v_pk_mul_f32 v[142:143], v[22:23], v[142:143]
	global_store_dwordx4 v5, v[128:131], s[56:57] nt
	global_store_dwordx4 v5, v[132:135], s[56:57] offset:16 nt
	global_store_dwordx4 v5, v[136:139], s[56:57] offset:2048 nt
	global_store_dwordx4 v5, v[140:143], s[56:57] offset:2064 nt
	s_add_i32 s58, s58, s38
	s_lshl_b32 s59, s58, 12
	s_add_u32 s56, s48, s59
	s_addc_u32 s57, s49, 0
	v_mov_b32_e32 v6, s63
	v_fmamk_f32 v6, v6, 0x3a800000, v24
	v_rsq_f32_e32 v6, v6
	s_waitcnt vmcnt(20)
	v_lshlrev_b32_e32 v144, 16, v56
	v_and_b32_e32 v145, 0xffff0000, v56
	v_lshlrev_b32_e32 v146, 16, v57
	v_and_b32_e32 v147, 0xffff0000, v57
	v_lshlrev_b32_e32 v148, 16, v58
	v_and_b32_e32 v149, 0xffff0000, v58
	v_lshlrev_b32_e32 v150, 16, v59
	v_and_b32_e32 v151, 0xffff0000, v59
	v_lshlrev_b32_e32 v152, 16, v60
	v_and_b32_e32 v153, 0xffff0000, v60
	v_lshlrev_b32_e32 v154, 16, v61
	v_and_b32_e32 v155, 0xffff0000, v61
	v_lshlrev_b32_e32 v156, 16, v62
	v_and_b32_e32 v157, 0xffff0000, v62
	v_lshlrev_b32_e32 v158, 16, v63
	v_and_b32_e32 v159, 0xffff0000, v63
	v_pk_mul_f32 v[144:145], v[6:7], v[144:145] op_sel_hi:[0,1]
	v_pk_mul_f32 v[146:147], v[6:7], v[146:147] op_sel_hi:[0,1]
	v_pk_mul_f32 v[148:149], v[6:7], v[148:149] op_sel_hi:[0,1]
	v_pk_mul_f32 v[150:151], v[6:7], v[150:151] op_sel_hi:[0,1]
	v_pk_mul_f32 v[152:153], v[6:7], v[152:153] op_sel_hi:[0,1]
	v_pk_mul_f32 v[154:155], v[6:7], v[154:155] op_sel_hi:[0,1]
	v_pk_mul_f32 v[156:157], v[6:7], v[156:157] op_sel_hi:[0,1]
	v_pk_mul_f32 v[158:159], v[6:7], v[158:159] op_sel_hi:[0,1]
	v_pk_mul_f32 v[144:145], v[8:9], v[144:145]
	v_pk_mul_f32 v[146:147], v[10:11], v[146:147]
	v_pk_mul_f32 v[148:149], v[12:13], v[148:149]
	v_pk_mul_f32 v[150:151], v[14:15], v[150:151]
	v_pk_mul_f32 v[152:153], v[16:17], v[152:153]
	v_pk_mul_f32 v[154:155], v[18:19], v[154:155]
	v_pk_mul_f32 v[156:157], v[20:21], v[156:157]
	v_pk_mul_f32 v[158:159], v[22:23], v[158:159]
	global_store_dwordx4 v5, v[144:147], s[56:57] nt
	global_store_dwordx4 v5, v[148:151], s[56:57] offset:16 nt
	global_store_dwordx4 v5, v[152:155], s[56:57] offset:2048 nt
	global_store_dwordx4 v5, v[156:159], s[56:57] offset:2064 nt
	s_add_i32 s58, s58, s38
	s_lshl_b32 s59, s58, 12
	s_add_u32 s56, s48, s59
	s_addc_u32 s57, s49, 0
	v_mov_b32_e32 v6, s64
	v_fmamk_f32 v6, v6, 0x3a800000, v24
	v_rsq_f32_e32 v6, v6
	s_waitcnt vmcnt(22)
	v_lshlrev_b32_e32 v160, 16, v64
	v_and_b32_e32 v161, 0xffff0000, v64
	v_lshlrev_b32_e32 v162, 16, v65
	v_and_b32_e32 v163, 0xffff0000, v65
	v_lshlrev_b32_e32 v164, 16, v66
	v_and_b32_e32 v165, 0xffff0000, v66
	v_lshlrev_b32_e32 v166, 16, v67
	v_and_b32_e32 v167, 0xffff0000, v67
	v_lshlrev_b32_e32 v168, 16, v68
	v_and_b32_e32 v169, 0xffff0000, v68
	v_lshlrev_b32_e32 v170, 16, v69
	v_and_b32_e32 v171, 0xffff0000, v69
	v_lshlrev_b32_e32 v172, 16, v70
	v_and_b32_e32 v173, 0xffff0000, v70
	v_lshlrev_b32_e32 v174, 16, v71
	v_and_b32_e32 v175, 0xffff0000, v71
	v_pk_mul_f32 v[160:161], v[6:7], v[160:161] op_sel_hi:[0,1]
	v_pk_mul_f32 v[162:163], v[6:7], v[162:163] op_sel_hi:[0,1]
	v_pk_mul_f32 v[164:165], v[6:7], v[164:165] op_sel_hi:[0,1]
	v_pk_mul_f32 v[166:167], v[6:7], v[166:167] op_sel_hi:[0,1]
	v_pk_mul_f32 v[168:169], v[6:7], v[168:169] op_sel_hi:[0,1]
	v_pk_mul_f32 v[170:171], v[6:7], v[170:171] op_sel_hi:[0,1]
	v_pk_mul_f32 v[172:173], v[6:7], v[172:173] op_sel_hi:[0,1]
	v_pk_mul_f32 v[174:175], v[6:7], v[174:175] op_sel_hi:[0,1]
	v_pk_mul_f32 v[160:161], v[8:9], v[160:161]
	v_pk_mul_f32 v[162:163], v[10:11], v[162:163]
	v_pk_mul_f32 v[164:165], v[12:13], v[164:165]
	v_pk_mul_f32 v[166:167], v[14:15], v[166:167]
	v_pk_mul_f32 v[168:169], v[16:17], v[168:169]
	v_pk_mul_f32 v[170:171], v[18:19], v[170:171]
	v_pk_mul_f32 v[172:173], v[20:21], v[172:173]
	v_pk_mul_f32 v[174:175], v[22:23], v[174:175]
	global_store_dwordx4 v5, v[160:163], s[56:57] nt
	global_store_dwordx4 v5, v[164:167], s[56:57] offset:16 nt
	global_store_dwordx4 v5, v[168:171], s[56:57] offset:2048 nt
	global_store_dwordx4 v5, v[172:175], s[56:57] offset:2064 nt
	s_add_i32 s58, s58, s38
	s_lshl_b32 s59, s58, 12
	s_add_u32 s56, s48, s59
	s_addc_u32 s57, s49, 0
	v_mov_b32_e32 v6, s65
	v_fmamk_f32 v6, v6, 0x3a800000, v24
	v_rsq_f32_e32 v6, v6
	s_waitcnt vmcnt(24)
	v_lshlrev_b32_e32 v176, 16, v72
	v_and_b32_e32 v177, 0xffff0000, v72
	v_lshlrev_b32_e32 v178, 16, v73
	v_and_b32_e32 v179, 0xffff0000, v73
	v_lshlrev_b32_e32 v180, 16, v74
	v_and_b32_e32 v181, 0xffff0000, v74
	v_lshlrev_b32_e32 v182, 16, v75
	v_and_b32_e32 v183, 0xffff0000, v75
	v_lshlrev_b32_e32 v184, 16, v76
	v_and_b32_e32 v185, 0xffff0000, v76
	v_lshlrev_b32_e32 v186, 16, v77
	v_and_b32_e32 v187, 0xffff0000, v77
	v_lshlrev_b32_e32 v188, 16, v78
	v_and_b32_e32 v189, 0xffff0000, v78
	v_lshlrev_b32_e32 v190, 16, v79
	v_and_b32_e32 v191, 0xffff0000, v79
	v_pk_mul_f32 v[176:177], v[6:7], v[176:177] op_sel_hi:[0,1]
	v_pk_mul_f32 v[178:179], v[6:7], v[178:179] op_sel_hi:[0,1]
	v_pk_mul_f32 v[180:181], v[6:7], v[180:181] op_sel_hi:[0,1]
	v_pk_mul_f32 v[182:183], v[6:7], v[182:183] op_sel_hi:[0,1]
	v_pk_mul_f32 v[184:185], v[6:7], v[184:185] op_sel_hi:[0,1]
	v_pk_mul_f32 v[186:187], v[6:7], v[186:187] op_sel_hi:[0,1]
	v_pk_mul_f32 v[188:189], v[6:7], v[188:189] op_sel_hi:[0,1]
	v_pk_mul_f32 v[190:191], v[6:7], v[190:191] op_sel_hi:[0,1]
	v_pk_mul_f32 v[176:177], v[8:9], v[176:177]
	v_pk_mul_f32 v[178:179], v[10:11], v[178:179]
	v_pk_mul_f32 v[180:181], v[12:13], v[180:181]
	v_pk_mul_f32 v[182:183], v[14:15], v[182:183]
	v_pk_mul_f32 v[184:185], v[16:17], v[184:185]
	v_pk_mul_f32 v[186:187], v[18:19], v[186:187]
	v_pk_mul_f32 v[188:189], v[20:21], v[188:189]
	v_pk_mul_f32 v[190:191], v[22:23], v[190:191]
	global_store_dwordx4 v5, v[176:179], s[56:57] nt
	global_store_dwordx4 v5, v[180:183], s[56:57] offset:16 nt
	global_store_dwordx4 v5, v[184:187], s[56:57] offset:2048 nt
	global_store_dwordx4 v5, v[188:191], s[56:57] offset:2064 nt
	s_add_i32 s58, s58, s38
	s_lshl_b32 s59, s58, 12
	s_add_u32 s56, s48, s59
	s_addc_u32 s57, s49, 0
	v_mov_b32_e32 v6, s66
	v_fmamk_f32 v6, v6, 0x3a800000, v24
	v_rsq_f32_e32 v6, v6
	s_waitcnt vmcnt(26)
	v_lshlrev_b32_e32 v192, 16, v80
	v_and_b32_e32 v193, 0xffff0000, v80
	v_lshlrev_b32_e32 v194, 16, v81
	v_and_b32_e32 v195, 0xffff0000, v81
	v_lshlrev_b32_e32 v196, 16, v82
	v_and_b32_e32 v197, 0xffff0000, v82
	v_lshlrev_b32_e32 v198, 16, v83
	v_and_b32_e32 v199, 0xffff0000, v83
	v_lshlrev_b32_e32 v200, 16, v84
	v_and_b32_e32 v201, 0xffff0000, v84
	v_lshlrev_b32_e32 v202, 16, v85
	v_and_b32_e32 v203, 0xffff0000, v85
	v_lshlrev_b32_e32 v204, 16, v86
	v_and_b32_e32 v205, 0xffff0000, v86
	v_lshlrev_b32_e32 v206, 16, v87
	v_and_b32_e32 v207, 0xffff0000, v87
	v_pk_mul_f32 v[192:193], v[6:7], v[192:193] op_sel_hi:[0,1]
	v_pk_mul_f32 v[194:195], v[6:7], v[194:195] op_sel_hi:[0,1]
	v_pk_mul_f32 v[196:197], v[6:7], v[196:197] op_sel_hi:[0,1]
	v_pk_mul_f32 v[198:199], v[6:7], v[198:199] op_sel_hi:[0,1]
	v_pk_mul_f32 v[200:201], v[6:7], v[200:201] op_sel_hi:[0,1]
	v_pk_mul_f32 v[202:203], v[6:7], v[202:203] op_sel_hi:[0,1]
	v_pk_mul_f32 v[204:205], v[6:7], v[204:205] op_sel_hi:[0,1]
	v_pk_mul_f32 v[206:207], v[6:7], v[206:207] op_sel_hi:[0,1]
	v_pk_mul_f32 v[192:193], v[8:9], v[192:193]
	v_pk_mul_f32 v[194:195], v[10:11], v[194:195]
	v_pk_mul_f32 v[196:197], v[12:13], v[196:197]
	v_pk_mul_f32 v[198:199], v[14:15], v[198:199]
	v_pk_mul_f32 v[200:201], v[16:17], v[200:201]
	v_pk_mul_f32 v[202:203], v[18:19], v[202:203]
	v_pk_mul_f32 v[204:205], v[20:21], v[204:205]
	v_pk_mul_f32 v[206:207], v[22:23], v[206:207]
	global_store_dwordx4 v5, v[192:195], s[56:57] nt
	global_store_dwordx4 v5, v[196:199], s[56:57] offset:16 nt
	global_store_dwordx4 v5, v[200:203], s[56:57] offset:2048 nt
	global_store_dwordx4 v5, v[204:207], s[56:57] offset:2064 nt
	s_add_i32 s58, s58, s38
	s_lshl_b32 s59, s58, 12
	s_add_u32 s56, s48, s59
	s_addc_u32 s57, s49, 0
	v_mov_b32_e32 v6, s67
	v_fmamk_f32 v6, v6, 0x3a800000, v24
	v_rsq_f32_e32 v6, v6
	s_waitcnt vmcnt(28)
	v_lshlrev_b32_e32 v208, 16, v88
	v_and_b32_e32 v209, 0xffff0000, v88
	v_lshlrev_b32_e32 v210, 16, v89
	v_and_b32_e32 v211, 0xffff0000, v89
	v_lshlrev_b32_e32 v212, 16, v90
	v_and_b32_e32 v213, 0xffff0000, v90
	v_lshlrev_b32_e32 v214, 16, v91
	v_and_b32_e32 v215, 0xffff0000, v91
	v_lshlrev_b32_e32 v216, 16, v92
	v_and_b32_e32 v217, 0xffff0000, v92
	v_lshlrev_b32_e32 v218, 16, v93
	v_and_b32_e32 v219, 0xffff0000, v93
	v_lshlrev_b32_e32 v220, 16, v94
	v_and_b32_e32 v221, 0xffff0000, v94
	v_lshlrev_b32_e32 v222, 16, v95
	v_and_b32_e32 v223, 0xffff0000, v95
	v_pk_mul_f32 v[208:209], v[6:7], v[208:209] op_sel_hi:[0,1]
	v_pk_mul_f32 v[210:211], v[6:7], v[210:211] op_sel_hi:[0,1]
	v_pk_mul_f32 v[212:213], v[6:7], v[212:213] op_sel_hi:[0,1]
	v_pk_mul_f32 v[214:215], v[6:7], v[214:215] op_sel_hi:[0,1]
	v_pk_mul_f32 v[216:217], v[6:7], v[216:217] op_sel_hi:[0,1]
	v_pk_mul_f32 v[218:219], v[6:7], v[218:219] op_sel_hi:[0,1]
	v_pk_mul_f32 v[220:221], v[6:7], v[220:221] op_sel_hi:[0,1]
	v_pk_mul_f32 v[222:223], v[6:7], v[222:223] op_sel_hi:[0,1]
	v_pk_mul_f32 v[208:209], v[8:9], v[208:209]
	v_pk_mul_f32 v[210:211], v[10:11], v[210:211]
	v_pk_mul_f32 v[212:213], v[12:13], v[212:213]
	v_pk_mul_f32 v[214:215], v[14:15], v[214:215]
	v_pk_mul_f32 v[216:217], v[16:17], v[216:217]
	v_pk_mul_f32 v[218:219], v[18:19], v[218:219]
	v_pk_mul_f32 v[220:221], v[20:21], v[220:221]
	v_pk_mul_f32 v[222:223], v[22:23], v[222:223]
	global_store_dwordx4 v5, v[208:211], s[56:57] nt
	global_store_dwordx4 v5, v[212:215], s[56:57] offset:16 nt
	global_store_dwordx4 v5, v[216:219], s[56:57] offset:2048 nt
	global_store_dwordx4 v5, v[220:223], s[56:57] offset:2064 nt
	s_lshl_b32 s15, s38, 3
	s_add_i32 s14, s14, s15
	s_branch .Lfn_loop
.Lfn_try4:
	s_mul_i32 s15, s38, 3
	s_add_i32 s15, s15, s14
	s_cmpk_lt_i32 s15, 0x4200
	s_cbranch_scc0 .Lfn_one
	s_mov_b32 s58, s14
	s_lshl_b32 s59, s58, 11
	s_add_u32 s56, s46, s59
	s_addc_u32 s57, s47, 0
	s_lshl_b32 s59, s58, 2
	s_load_dword s60, s[52:53], s59
	global_load_dwordx4 v[32:35], v4, s[56:57]
	global_load_dwordx4 v[36:39], v4, s[56:57] offset:1024
	s_add_i32 s58, s58, s38
	s_lshl_b32 s59, s58, 11
	s_add_u32 s56, s46, s59
	s_addc_u32 s57, s47, 0
	s_lshl_b32 s59, s58, 2
	s_load_dword s61, s[52:53], s59
	global_load_dwordx4 v[40:43], v4, s[56:57]
	global_load_dwordx4 v[44:47], v4, s[56:57] offset:1024
	s_add_i32 s58, s58, s38
	s_lshl_b32 s59, s58, 11
	s_add_u32 s56, s46, s59
	s_addc_u32 s57, s47, 0
	s_lshl_b32 s59, s58, 2
	s_load_dword s62, s[52:53], s59
	global_load_dwordx4 v[48:51], v4, s[56:57]
	global_load_dwordx4 v[52:55], v4, s[56:57] offset:1024
	s_add_i32 s58, s58, s38
	s_lshl_b32 s59, s58, 11
	s_add_u32 s56, s46, s59
	s_addc_u32 s57, s47, 0
	s_lshl_b32 s59, s58, 2
	s_load_dword s63, s[52:53], s59
	global_load_dwordx4 v[56:59], v4, s[56:57]
	global_load_dwordx4 v[60:63], v4, s[56:57] offset:1024
	s_waitcnt lgkmcnt(0)
	s_mov_b32 s58, s14
	s_lshl_b32 s59, s58, 12
	s_add_u32 s56, s48, s59
	s_addc_u32 s57, s49, 0
	v_mov_b32_e32 v6, s60
	v_fmamk_f32 v6, v6, 0x3a800000, v24
	v_rsq_f32_e32 v6, v6
	s_waitcnt vmcnt(6)
	v_lshlrev_b32_e32 v96, 16, v32
	v_and_b32_e32 v97, 0xffff0000, v32
	v_lshlrev_b32_e32 v98, 16, v33
	v_and_b32_e32 v99, 0xffff0000, v33
	v_lshlrev_b32_e32 v100, 16, v34
	v_and_b32_e32 v101, 0xffff0000, v34
	v_lshlrev_b32_e32 v102, 16, v35
	v_and_b32_e32 v103, 0xffff0000, v35
	v_lshlrev_b32_e32 v104, 16, v36
	v_and_b32_e32 v105, 0xffff0000, v36
	v_lshlrev_b32_e32 v106, 16, v37
	v_and_b32_e32 v107, 0xffff0000, v37
	v_lshlrev_b32_e32 v108, 16, v38
	v_and_b32_e32 v109, 0xffff0000, v38
	v_lshlrev_b32_e32 v110, 16, v39
	v_and_b32_e32 v111, 0xffff0000, v39
	v_pk_mul_f32 v[96:97], v[6:7], v[96:97] op_sel_hi:[0,1]
	v_pk_mul_f32 v[98:99], v[6:7], v[98:99] op_sel_hi:[0,1]
	v_pk_mul_f32 v[100:101], v[6:7], v[100:101] op_sel_hi:[0,1]
	v_pk_mul_f32 v[102:103], v[6:7], v[102:103] op_sel_hi:[0,1]
	v_pk_mul_f32 v[104:105], v[6:7], v[104:105] op_sel_hi:[0,1]
	v_pk_mul_f32 v[106:107], v[6:7], v[106:107] op_sel_hi:[0,1]
	v_pk_mul_f32 v[108:109], v[6:7], v[108:109] op_sel_hi:[0,1]
	v_pk_mul_f32 v[110:111], v[6:7], v[110:111] op_sel_hi:[0,1]
	v_pk_mul_f32 v[96:97], v[8:9], v[96:97]
	v_pk_mul_f32 v[98:99], v[10:11], v[98:99]
	v_pk_mul_f32 v[100:101], v[12:13], v[100:101]
	v_pk_mul_f32 v[102:103], v[14:15], v[102:103]
	v_pk_mul_f32 v[104:105], v[16:17], v[104:105]
	v_pk_mul_f32 v[106:107], v[18:19], v[106:107]
	v_pk_mul_f32 v[108:109], v[20:21], v[108:109]
	v_pk_mul_f32 v[110:111], v[22:23], v[110:111]
	global_store_dwordx4 v5, v[96:99], s[56:57] nt
	global_store_dwordx4 v5, v[100:103], s[56:57] offset:16 nt
	global_store_dwordx4 v5, v[104:107], s[56:57] offset:2048 nt
	global_store_dwordx4 v5, v[108:111], s[56:57] offset:2064 nt
	s_add_i32 s58, s58, s38
	s_lshl_b32 s59, s58, 12
	s_add_u32 s56, s48, s59
	s_addc_u32 s57, s49, 0
	v_mov_b32_e32 v6, s61
	v_fmamk_f32 v6, v6, 0x3a800000, v24
	v_rsq_f32_e32 v6, v6
	s_waitcnt vmcnt(8)
	v_lshlrev_b32_e32 v112, 16, v40
	v_and_b32_e32 v113, 0xffff0000, v40
	v_lshlrev_b32_e32 v114, 16, v41
	v_and_b32_e32 v115, 0xffff0000, v41
	v_lshlrev_b32_e32 v116, 16, v42
	v_and_b32_e32 v117, 0xffff0000, v42
	v_lshlrev_b32_e32 v118, 16, v43
	v_and_b32_e32 v119, 0xffff0000, v43
	v_lshlrev_b32_e32 v120, 16, v44
	v_and_b32_e32 v121, 0xffff0000, v44
	v_lshlrev_b32_e32 v122, 16, v45
	v_and_b32_e32 v123, 0xffff0000, v45
	v_lshlrev_b32_e32 v124, 16, v46
	v_and_b32_e32 v125, 0xffff0000, v46
	v_lshlrev_b32_e32 v126, 16, v47
	v_and_b32_e32 v127, 0xffff0000, v47
	v_pk_mul_f32 v[112:113], v[6:7], v[112:113] op_sel_hi:[0,1]
	v_pk_mul_f32 v[114:115], v[6:7], v[114:115] op_sel_hi:[0,1]
	v_pk_mul_f32 v[116:117], v[6:7], v[116:117] op_sel_hi:[0,1]
	v_pk_mul_f32 v[118:119], v[6:7], v[118:119] op_sel_hi:[0,1]
	v_pk_mul_f32 v[120:121], v[6:7], v[120:121] op_sel_hi:[0,1]
	v_pk_mul_f32 v[122:123], v[6:7], v[122:123] op_sel_hi:[0,1]
	v_pk_mul_f32 v[124:125], v[6:7], v[124:125] op_sel_hi:[0,1]
	v_pk_mul_f32 v[126:127], v[6:7], v[126:127] op_sel_hi:[0,1]
	v_pk_mul_f32 v[112:113], v[8:9], v[112:113]
	v_pk_mul_f32 v[114:115], v[10:11], v[114:115]
	v_pk_mul_f32 v[116:117], v[12:13], v[116:117]
	v_pk_mul_f32 v[118:119], v[14:15], v[118:119]
	v_pk_mul_f32 v[120:121], v[16:17], v[120:121]
	v_pk_mul_f32 v[122:123], v[18:19], v[122:123]
	v_pk_mul_f32 v[124:125], v[20:21], v[124:125]
	v_pk_mul_f32 v[126:127], v[22:23], v[126:127]
	global_store_dwordx4 v5, v[112:115], s[56:57] nt
	global_store_dwordx4 v5, v[116:119], s[56:57] offset:16 nt
	global_store_dwordx4 v5, v[120:123], s[56:57] offset:2048 nt
	global_store_dwordx4 v5, v[124:127], s[56:57] offset:2064 nt
	s_add_i32 s58, s58, s38
	s_lshl_b32 s59, s58, 12
	s_add_u32 s56, s48, s59
	s_addc_u32 s57, s49, 0
	v_mov_b32_e32 v6, s62
	v_fmamk_f32 v6, v6, 0x3a800000, v24
	v_rsq_f32_e32 v6, v6
	s_waitcnt vmcnt(10)
	v_lshlrev_b32_e32 v128, 16, v48
	v_and_b32_e32 v129, 0xffff0000, v48
	v_lshlrev_b32_e32 v130, 16, v49
	v_and_b32_e32 v131, 0xffff0000, v49
	v_lshlrev_b32_e32 v132, 16, v50
	v_and_b32_e32 v133, 0xffff0000, v50
	v_lshlrev_b32_e32 v134, 16, v51
	v_and_b32_e32 v135, 0xffff0000, v51
	v_lshlrev_b32_e32 v136, 16, v52
	v_and_b32_e32 v137, 0xffff0000, v52
	v_lshlrev_b32_e32 v138, 16, v53
	v_and_b32_e32 v139, 0xffff0000, v53
	v_lshlrev_b32_e32 v140, 16, v54
	v_and_b32_e32 v141, 0xffff0000, v54
	v_lshlrev_b32_e32 v142, 16, v55
	v_and_b32_e32 v143, 0xffff0000, v55
	v_pk_mul_f32 v[128:129], v[6:7], v[128:129] op_sel_hi:[0,1]
	v_pk_mul_f32 v[130:131], v[6:7], v[130:131] op_sel_hi:[0,1]
	v_pk_mul_f32 v[132:133], v[6:7], v[132:133] op_sel_hi:[0,1]
	v_pk_mul_f32 v[134:135], v[6:7], v[134:135] op_sel_hi:[0,1]
	v_pk_mul_f32 v[136:137], v[6:7], v[136:137] op_sel_hi:[0,1]
	v_pk_mul_f32 v[138:139], v[6:7], v[138:139] op_sel_hi:[0,1]
	v_pk_mul_f32 v[140:141], v[6:7], v[140:141] op_sel_hi:[0,1]
	v_pk_mul_f32 v[142:143], v[6:7], v[142:143] op_sel_hi:[0,1]
	v_pk_mul_f32 v[128:129], v[8:9], v[128:129]
	v_pk_mul_f32 v[130:131], v[10:11], v[130:131]
	v_pk_mul_f32 v[132:133], v[12:13], v[132:133]
	v_pk_mul_f32 v[134:135], v[14:15], v[134:135]
	v_pk_mul_f32 v[136:137], v[16:17], v[136:137]
	v_pk_mul_f32 v[138:139], v[18:19], v[138:139]
	v_pk_mul_f32 v[140:141], v[20:21], v[140:141]
	v_pk_mul_f32 v[142:143], v[22:23], v[142:143]
	global_store_dwordx4 v5, v[128:131], s[56:57] nt
	global_store_dwordx4 v5, v[132:135], s[56:57] offset:16 nt
	global_store_dwordx4 v5, v[136:139], s[56:57] offset:2048 nt
	global_store_dwordx4 v5, v[140:143], s[56:57] offset:2064 nt
	s_add_i32 s58, s58, s38
	s_lshl_b32 s59, s58, 12
	s_add_u32 s56, s48, s59
	s_addc_u32 s57, s49, 0
	v_mov_b32_e32 v6, s63
	v_fmamk_f32 v6, v6, 0x3a800000, v24
	v_rsq_f32_e32 v6, v6
	s_waitcnt vmcnt(12)
	v_lshlrev_b32_e32 v144, 16, v56
	v_and_b32_e32 v145, 0xffff0000, v56
	v_lshlrev_b32_e32 v146, 16, v57
	v_and_b32_e32 v147, 0xffff0000, v57
	v_lshlrev_b32_e32 v148, 16, v58
	v_and_b32_e32 v149, 0xffff0000, v58
	v_lshlrev_b32_e32 v150, 16, v59
	v_and_b32_e32 v151, 0xffff0000, v59
	v_lshlrev_b32_e32 v152, 16, v60
	v_and_b32_e32 v153, 0xffff0000, v60
	v_lshlrev_b32_e32 v154, 16, v61
	v_and_b32_e32 v155, 0xffff0000, v61
	v_lshlrev_b32_e32 v156, 16, v62
	v_and_b32_e32 v157, 0xffff0000, v62
	v_lshlrev_b32_e32 v158, 16, v63
	v_and_b32_e32 v159, 0xffff0000, v63
	v_pk_mul_f32 v[144:145], v[6:7], v[144:145] op_sel_hi:[0,1]
	v_pk_mul_f32 v[146:147], v[6:7], v[146:147] op_sel_hi:[0,1]
	v_pk_mul_f32 v[148:149], v[6:7], v[148:149] op_sel_hi:[0,1]
	v_pk_mul_f32 v[150:151], v[6:7], v[150:151] op_sel_hi:[0,1]
	v_pk_mul_f32 v[152:153], v[6:7], v[152:153] op_sel_hi:[0,1]
	v_pk_mul_f32 v[154:155], v[6:7], v[154:155] op_sel_hi:[0,1]
	v_pk_mul_f32 v[156:157], v[6:7], v[156:157] op_sel_hi:[0,1]
	v_pk_mul_f32 v[158:159], v[6:7], v[158:159] op_sel_hi:[0,1]
	v_pk_mul_f32 v[144:145], v[8:9], v[144:145]
	v_pk_mul_f32 v[146:147], v[10:11], v[146:147]
	v_pk_mul_f32 v[148:149], v[12:13], v[148:149]
	v_pk_mul_f32 v[150:151], v[14:15], v[150:151]
	v_pk_mul_f32 v[152:153], v[16:17], v[152:153]
	v_pk_mul_f32 v[154:155], v[18:19], v[154:155]
	v_pk_mul_f32 v[156:157], v[20:21], v[156:157]
	v_pk_mul_f32 v[158:159], v[22:23], v[158:159]
	global_store_dwordx4 v5, v[144:147], s[56:57] nt
	global_store_dwordx4 v5, v[148:151], s[56:57] offset:16 nt
	global_store_dwordx4 v5, v[152:155], s[56:57] offset:2048 nt
	global_store_dwordx4 v5, v[156:159], s[56:57] offset:2064 nt
	s_lshl_b32 s15, s38, 2
	s_add_i32 s14, s14, s15
	s_branch .Lfn_loop
.Lfn_one:
	s_mov_b32 s58, s14
	s_lshl_b32 s59, s58, 11
	s_add_u32 s56, s46, s59
	s_addc_u32 s57, s47, 0
	s_lshl_b32 s59, s58, 2
	s_load_dword s60, s[52:53], s59
	global_load_dwordx4 v[32:35], v4, s[56:57]
	global_load_dwordx4 v[36:39], v4, s[56:57] offset:1024
	s_waitcnt lgkmcnt(0)
	s_mov_b32 s58, s14
	s_lshl_b32 s59, s58, 12
	s_add_u32 s56, s48, s59
	s_addc_u32 s57, s49, 0
	v_mov_b32_e32 v6, s60
	v_fmamk_f32 v6, v6, 0x3a800000, v24
	v_rsq_f32_e32 v6, v6
	s_waitcnt vmcnt(0)
	v_lshlrev_b32_e32 v96, 16, v32
	v_and_b32_e32 v97, 0xffff0000, v32
	v_lshlrev_b32_e32 v98, 16, v33
	v_and_b32_e32 v99, 0xffff0000, v33
	v_lshlrev_b32_e32 v100, 16, v34
	v_and_b32_e32 v101, 0xffff0000, v34
	v_lshlrev_b32_e32 v102, 16, v35
	v_and_b32_e32 v103, 0xffff0000, v35
	v_lshlrev_b32_e32 v104, 16, v36
	v_and_b32_e32 v105, 0xffff0000, v36
	v_lshlrev_b32_e32 v106, 16, v37
	v_and_b32_e32 v107, 0xffff0000, v37
	v_lshlrev_b32_e32 v108, 16, v38
	v_and_b32_e32 v109, 0xffff0000, v38
	v_lshlrev_b32_e32 v110, 16, v39
	v_and_b32_e32 v111, 0xffff0000, v39
	v_pk_mul_f32 v[96:97], v[6:7], v[96:97] op_sel_hi:[0,1]
	v_pk_mul_f32 v[98:99], v[6:7], v[98:99] op_sel_hi:[0,1]
	v_pk_mul_f32 v[100:101], v[6:7], v[100:101] op_sel_hi:[0,1]
	v_pk_mul_f32 v[102:103], v[6:7], v[102:103] op_sel_hi:[0,1]
	v_pk_mul_f32 v[104:105], v[6:7], v[104:105] op_sel_hi:[0,1]
	v_pk_mul_f32 v[106:107], v[6:7], v[106:107] op_sel_hi:[0,1]
	v_pk_mul_f32 v[108:109], v[6:7], v[108:109] op_sel_hi:[0,1]
	v_pk_mul_f32 v[110:111], v[6:7], v[110:111] op_sel_hi:[0,1]
	v_pk_mul_f32 v[96:97], v[8:9], v[96:97]
	v_pk_mul_f32 v[98:99], v[10:11], v[98:99]
	v_pk_mul_f32 v[100:101], v[12:13], v[100:101]
	v_pk_mul_f32 v[102:103], v[14:15], v[102:103]
	v_pk_mul_f32 v[104:105], v[16:17], v[104:105]
	v_pk_mul_f32 v[106:107], v[18:19], v[106:107]
	v_pk_mul_f32 v[108:109], v[20:21], v[108:109]
	v_pk_mul_f32 v[110:111], v[22:23], v[110:111]
	global_store_dwordx4 v5, v[96:99], s[56:57] nt
	global_store_dwordx4 v5, v[100:103], s[56:57] offset:16 nt
	global_store_dwordx4 v5, v[104:107], s[56:57] offset:2048 nt
	global_store_dwordx4 v5, v[108:111], s[56:57] offset:2064 nt
	s_add_i32 s14, s14, s38
	s_branch .Lfn_loop
